# P3 prompt scan: each workgroup loads only its 64-column half of the V tile (exec-masked loads), on top of v7
# speedup vs baseline: 1.0141x; 1.0141x over previous
.LBB0_1198:
	s_and_b64 vcc, exec, s[2:3]
	s_cbranch_vccz .LBB0_1229
	s_ashr_i32 s8, s85, 4
	s_lshl_b32 s2, s85, 6
	s_bfe_u32 s16, s85, 0x30001
	s_bfe_u32 s12, s85, 0x20001
	s_lshl_b32 s10, s8, 11
	s_and_b32 s22, s2, 64
	s_lshr_b32 s100, s22, 6
	v_bfe_u32 v240, v1, 3, 1
	v_cmp_eq_u32_e64 s[100:101], v240, s100
	s_cmp_lt_u32 s16, 4
	s_cselect_b64 s[2:3], -1, 0
	s_lshl_b32 s4, s8, 2
	s_or_b32 s4, s4, s12
	s_ashr_i32 s5, s4, 31
	s_mov_b32 s9, 0x4400000
	s_and_b64 s[6:7], s[2:3], exec
	v_readlane_b32 s24, v255, 0
	s_cselect_b32 s6, s9, 0x4500000
	v_readlane_b32 s26, v255, 2
	v_readlane_b32 s27, v255, 3
	s_add_u32 s9, s26, s6
	s_addc_u32 s11, s27, 0
	s_and_b64 s[6:7], s[2:3], exec
	s_cselect_b32 s6, 15, 16
	s_lshl_b64 s[4:5], s[4:5], s6
	s_add_u32 s4, s9, s4
	s_addc_u32 s5, s11, s5
	s_ashr_i32 s11, s10, 31
	s_mul_i32 s6, s8, 0xe00000
	s_mul_hi_i32 s7, s10, 0x1c00
	s_add_u32 s6, s20, s6
	s_addc_u32 s7, s21, s7
	s_lshl_b32 s13, s12, 6
	s_lshl_b32 s12, s12, 7
	s_bitset1_b32 s13, 8
	s_bitset1_b32 s12, 11
	s_and_b64 s[2:3], s[2:3], exec
	s_cselect_b32 s2, s13, s12
	s_lshl_b32 s2, s2, 1
	s_add_u32 s14, s6, s2
	s_addc_u32 s15, s7, 0
	s_lshl_b32 s2, s8, 9
	s_or_b32 s2, s2, s16
	s_ashr_i32 s3, s2, 31
	s_lshl_b64 s[2:3], s[2:3], 9
	s_add_u32 s12, s62, s2
	s_addc_u32 s13, s63, s3
	s_lshl_b32 s8, s86, 4
	s_cmpk_lt_u32 s87, 0x100
	s_cselect_b64 s[6:7], -1, 0
	s_and_b64 s[2:3], s[6:7], exec
	s_cselect_b32 s23, s8, 0
	s_add_i32 s2, s23, s22
	v_and_b32_e32 v115, 15, v1
	v_lshrrev_b32_e32 v117, 4, v1
	s_lshl_b32 s8, s16, 7
	v_lshrrev_b32_e32 v112, 4, v254
	v_or_b32_e32 v98, s2, v115
	v_min_u32_e32 v2, 31, v117
	s_mov_b32 s17, 0
	s_movk_i32 s9, 0x1c00
	s_cmp_gt_u32 s16, 3
	s_mov_b64 s[2:3], -1
	v_lshlrev_b32_e32 v100, 4, v115
	v_or_b32_e32 v118, s10, v2
	v_lshl_add_u32 v113, v112, 3, 0
	v_lshl_add_u32 v114, v98, 1, 0
	v_or_b32_e32 v116, 48, v254
	v_readlane_b32 s25, v255, 1
	s_cbranch_scc0 .LBB0_1214
	v_bfe_u32 v10, v1, 4, 5
	s_lshl_b32 s18, s8, 1
	v_or_b32_e32 v4, s10, v10
	v_mov_b64_e32 v[2:3], s[20:21]
	v_mad_i64_i32 v[4:5], s[2:3], v4, s9, v[2:3]
	s_or_b32 s16, s18, 0xc00
	v_lshl_add_u64 v[4:5], v[4:5], 0, s[16:17]
	v_mov_b32_e32 v101, 0
	v_lshl_add_u64 v[102:103], v[4:5], 0, v[100:101]
	v_mul_u32_u24_e32 v4, 0xe00, v10
	v_lshlrev_b32_e32 v4, 1, v4
	v_mov_b32_e32 v5, v101
	v_mad_i64_i32 v[2:3], s[2:3], v118, s9, v[2:3]
	s_or_b32 s16, s18, 0x1400
	v_and_b32_e32 v6, 31, v1
	v_lshl_add_u64 v[4:5], s[14:15], 0, v[4:5]
	v_lshl_add_u64 v[2:3], v[2:3], 0, s[16:17]
	v_lshl_add_u64 v[104:105], v[4:5], 0, v[100:101]
	v_lshlrev_b32_e32 v4, 4, v6
	v_lshl_add_u64 v[106:107], v[2:3], 0, v[100:101]
	global_load_dwordx4 v[18:21], v[102:103], off
	global_load_dwordx4 v[22:25], v[104:105], off
	global_load_dwordx4 v[26:29], v4, s[12:13]
	global_load_dwordx4 v[30:33], v[106:107], off
	v_mov_b32_e32 v5, v101
	s_movk_i32 s2, 0x2000
	v_lshl_add_u64 v[108:109], s[12:13], 0, v[4:5]
	v_add_co_u32_e32 v2, vcc, s2, v108
	s_mov_b32 s9, 0x38000
	s_nop 0
	v_addc_co_u32_e32 v3, vcc, 0, v109, vcc
	v_add_co_u32_e32 v6, vcc, s9, v102
	global_load_dwordx4 v[42:45], v[2:3], off offset:-4096
	s_nop 0
	v_addc_co_u32_e32 v7, vcc, 0, v103, vcc
	v_add_co_u32_e32 v8, vcc, s9, v104
	s_movk_i32 s2, 0x110
	s_nop 0
	v_addc_co_u32_e32 v9, vcc, 0, v105, vcc
	global_load_dwordx4 v[54:57], v[6:7], off
	global_load_dwordx4 v[58:61], v[8:9], off
	v_add_co_u32_e32 v6, vcc, s9, v106
	v_bfe_u32 v5, v1, 2, 7
	s_nop 0
	v_addc_co_u32_e32 v7, vcc, 0, v107, vcc
	global_load_dwordx4 v[62:65], v[6:7], off
	s_movk_i32 s3, 0x50
	v_lshlrev_b32_e32 v6, 4, v1
	s_mov_b32 s16, 0x70000
	v_mad_u32_u24 v7, v10, s2, 0
	v_mad_u32_u24 v5, v5, s3, 0
	v_and_b32_e32 v6, 48, v6
	v_mad_u32_u24 v8, v117, s2, 0
	v_add_u32_e32 v99, v7, v100
	v_add_u32_e32 v119, v5, v6
	v_add_u32_e32 v121, v8, v100
	global_load_dwordx4 v[6:9], v[2:3], off
	v_add_co_u32_e32 v2, vcc, s16, v102
	s_mov_b32 s18, 0xe0000
	s_nop 0
	v_addc_co_u32_e32 v3, vcc, 0, v103, vcc
	v_add_co_u32_e32 v10, vcc, s16, v104
	v_add_u32_e32 v120, 0, v4
	s_nop 0
	v_addc_co_u32_e32 v11, vcc, 0, v105, vcc
	v_add_co_u32_e32 v14, vcc, s18, v106
	global_load_dwordx4 v[2:5], v[2:3], off
	s_nop 0
	global_load_dwordx4 v[10:13], v[10:11], off
	v_addc_co_u32_e32 v15, vcc, 0, v107, vcc
	global_load_dwordx4 v[14:17], v[14:15], off
	s_mov_b32 s2, 0xa8000
	s_movk_i32 s3, 0x4000
	s_movk_i32 s24, 0x1000
	s_mov_b32 s25, 0x8000
	s_mov_b32 s26, 0x9000
	s_mov_b32 s27, 0x10000
	s_mov_b32 s28, 0x11000
	s_mov_b32 s29, 0x18000
	s_mov_b32 s30, 0x19000
	s_mov_b32 s31, 0x20000
	s_mov_b32 s33, 0x21000
	s_mov_b32 s34, 0x28000
	s_waitcnt vmcnt(0)
	ds_write_b128 v99, v[18:21]
	ds_write_b128 v119, v[22:25] offset:8704
	ds_write_b128 v120, v[26:29] offset:18944
	ds_write_b128 v121, v[30:33] offset:19456
	v_add_co_u32_e32 v18, vcc, s16, v106
	s_mov_b32 s35, 0x29000
	s_nop 0
	v_addc_co_u32_e32 v19, vcc, 0, v107, vcc
	v_add_co_u32_e32 v20, vcc, s2, v102
	s_mov_b32 s36, 0x30000
	s_nop 0
	v_addc_co_u32_e32 v21, vcc, 0, v103, vcc
	v_add_co_u32_e32 v26, vcc, s2, v104
	global_load_dwordx4 v[22:25], v[18:19], off
	s_nop 0
	global_load_dwordx4 v[18:21], v[20:21], off
	v_addc_co_u32_e32 v27, vcc, 0, v105, vcc
	v_add_co_u32_e32 v50, vcc, s3, v108
	s_mov_b32 s37, 0x31000
	s_nop 0
	v_addc_co_u32_e32 v51, vcc, 0, v109, vcc
	v_add_co_u32_e32 v30, vcc, s2, v106
	s_lshl_b64 s[2:3], s[10:11], 11
	s_nop 0
	v_addc_co_u32_e32 v31, vcc, 0, v107, vcc
	global_load_dwordx4 v[26:29], v[26:27], off
	s_nop 0
	global_load_dwordx4 v[38:41], v[30:31], off
	v_add_co_u32_e32 v30, vcc, s18, v102
	s_mov_b32 s38, 0x39000
	s_nop 0
	v_addc_co_u32_e32 v31, vcc, 0, v103, vcc
	v_add_co_u32_e32 v34, vcc, s18, v104
	s_mov_b64 s[18:19], 0x40000
	s_nop 0
	v_addc_co_u32_e32 v35, vcc, 0, v105, vcc
	global_load_dwordx4 v[30:33], v[30:31], off
	s_nop 0
	global_load_dwordx4 v[34:37], v[34:35], off
	s_nop 0
	global_load_dwordx4 v[46:49], v[50:51], off offset:-4096
	s_nop 0
	global_load_dwordx4 v[50:53], v[50:51], off
	ds_write_b128 v99, v[54:57] offset:28160
	ds_write_b128 v119, v[58:61] offset:36864
	ds_write_b128 v120, v[42:45] offset:47104
	ds_write_b128 v121, v[62:65] offset:47616
	v_and_b32_e32 v42, 48, v1
	v_or_b32_e32 v43, 0x70, v254
	v_add_u32_e32 v122, 0, v42
	v_mul_u32_u24_e32 v58, 0x50, v43
	v_lshlrev_b32_e32 v42, 9, v42
	v_mov_b32_e32 v43, v101
	v_lshl_add_u64 v[42:43], v[42:43], 0, s[2:3]
	s_add_i32 s2, s23, s8
	s_add_i32 s2, s2, s22
	v_add_u32_e32 v44, s2, v115
	v_mov_b32_e32 v45, v101
	s_waitcnt lgkmcnt(0)
	s_barrier
	v_lshl_add_u64 v[42:43], v[44:45], 1, v[42:43]
	v_mul_u32_u24_e32 v54, 0x110, v115
	v_mul_u32_u24_e32 v55, 0x880, v112
	v_mul_u32_u24_e32 v56, 0x50, v115
	v_mul_u32_u24_e32 v57, 0x50, v116
	v_lshl_add_u64 v[42:43], s[46:47], 0, v[42:43]
	s_mov_b64 s[2:3], 0x4f00000
	v_lshl_add_u64 v[110:111], v[42:43], 0, s[2:3]
	v_add_u32_e32 v123, v113, v54
	v_add_u32_e32 v124, v114, v55
	v_add_u32_e32 v125, v122, v56
	v_add_u32_e32 v126, v122, v57
	v_add_u32_e32 v127, v122, v58
	s_mov_b32 s39, 0
	v_mov_b32_e32 v70, v101
	v_mov_b32_e32 v71, v101
	v_mov_b32_e32 v72, v101
	v_mov_b32_e32 v73, v101
	v_mov_b32_e32 v66, v101
	v_mov_b32_e32 v67, v101
	v_mov_b32_e32 v68, v101
	v_mov_b32_e32 v69, v101
	v_mov_b32_e32 v74, v101
	v_mov_b32_e32 v75, v101
	v_mov_b32_e32 v76, v101
	v_mov_b32_e32 v77, v101
	v_mov_b32_e32 v78, v101
	v_mov_b32_e32 v79, v101
	v_mov_b32_e32 v80, v101
	v_mov_b32_e32 v81, v101
	v_mov_b32_e32 v62, v101
	v_mov_b32_e32 v63, v101
	v_mov_b32_e32 v64, v101
	v_mov_b32_e32 v65, v101
	v_mov_b32_e32 v54, v101
	v_mov_b32_e32 v55, v101
	v_mov_b32_e32 v56, v101
	v_mov_b32_e32 v57, v101
	v_mov_b32_e32 v42, v101
	v_mov_b32_e32 v43, v101
	v_mov_b32_e32 v44, v101
	v_mov_b32_e32 v58, v101
	v_mov_b32_e32 v59, v101
	v_mov_b32_e32 v60, v101
	v_mov_b32_e32 v61, v101
.LBB0_1201:
	s_min_u32 s2, s39, 58
	s_add_i32 s2, s2, 5
	s_mul_i32 s16, s2, 0x38000
	s_lshl_b32 s2, s2, 12
	s_mov_b32 s3, s17
	v_lshl_add_u64 v[82:83], v[102:103], 0, s[16:17]
	v_lshl_add_u64 v[86:87], v[104:105], 0, s[16:17]
	v_lshl_add_u64 v[90:91], v[108:109], 0, s[2:3]
	v_lshl_add_u64 v[94:95], v[106:107], 0, s[16:17]
	global_load_dwordx4 v[82:85], v[82:83], off
	s_nop 0
	global_load_dwordx4 v[86:89], v[86:87], off
	s_nop 0
	global_load_dwordx4 v[90:93], v[90:91], off
	s_nop 0
	s_mov_b64 exec, s[100:101]
	global_load_dwordx4 v[94:97], v[94:95], off
	s_mov_b64 exec, -1
	v_cndmask_b32_e64 v101, 0, 1, s[6:7]
	v_cmp_ne_u32_e64 s[2:3], 1, v101
	s_andn2_b64 vcc, exec, s[6:7]
	v_add_u32_e32 v129, 0x1000, v123
	s_cbranch_vccnz .LBB0_1203
	s_setprio 2
	v_add_u32_e32 v160, 0x1000, v123
	ds_read2_b64 v[128:131], v123 offset1:4
	ds_read2_b64 v[132:135], v160 offset0:32 offset1:36
	ds_read2_b64 v[136:139], v123 offset0:8 offset1:12
	ds_read2_b64 v[140:143], v160 offset0:40 offset1:44
	ds_read2_b64 v[144:147], v123 offset0:16 offset1:20
	ds_read2_b64 v[148:151], v160 offset0:48 offset1:52
	ds_read2_b64 v[152:155], v123 offset0:24 offset1:28
	ds_read2_b64 v[156:159], v160 offset0:56 offset1:60
	ds_read_u16 v161, v124 offset:19456
	ds_read_u16 v184, v124 offset:19728
	ds_read_u16 v185, v124 offset:20000
	ds_read_u16 v186, v124 offset:20272
	ds_read_u16 v179, v124 offset:20544
	ds_read_u16 v252, v124 offset:20816
	v_cvt_pk_bf16_f32 v162, v70, v71
	v_cvt_pk_bf16_f32 v163, v72, v73
	v_cvt_pk_bf16_f32 v164, v66, v67
	v_cvt_pk_bf16_f32 v165, v68, v69
	s_waitcnt lgkmcnt(13)
	s_nop 0
	v_mfma_f32_16x16x32_bf16 v[170:173], v[128:131], v[162:165], 0
	s_waitcnt lgkmcnt(12)
	v_mfma_f32_16x16x32_bf16 v[174:177], v[132:135], v[162:165], 0
	ds_read_u16 v253, v124 offset:21088
	ds_read_u16 v208, v124 offset:21360
	ds_read_b128 v[180:183], v125 offset:8704
	v_cvt_pk_bf16_f32 v166, v74, v75
	v_cvt_pk_bf16_f32 v167, v76, v77
	v_cvt_pk_bf16_f32 v168, v78, v79
	v_cvt_pk_bf16_f32 v169, v80, v81
	s_waitcnt lgkmcnt(14)
	s_nop 0
	v_mfma_f32_16x16x32_bf16 v[170:173], v[136:139], v[166:169], v[170:173]
	s_waitcnt lgkmcnt(13)
	v_mfma_f32_16x16x32_bf16 v[174:177], v[140:143], v[166:169], v[174:177]
	ds_read_b128 v[188:191], v122 offset:18944
	ds_read_b128 v[192:195], v125 offset:9984
	v_cvt_pk_bf16_f32 v162, v62, v63
	v_cvt_pk_bf16_f32 v163, v64, v65
	v_cvt_pk_bf16_f32 v164, v54, v55
	v_cvt_pk_bf16_f32 v165, v56, v57
	s_waitcnt lgkmcnt(14)
	s_nop 0
	v_mfma_f32_16x16x32_bf16 v[170:173], v[144:147], v[162:165], v[170:173]
	s_waitcnt lgkmcnt(13)
	v_mfma_f32_16x16x32_bf16 v[174:177], v[148:151], v[162:165], v[174:177]
	ds_read_b128 v[232:235], v122 offset:19008
	ds_read_b128 v[236:239], v125 offset:11264
	v_cvt_pk_bf16_f32 v166, v42, v43
	v_cvt_pk_bf16_f32 v167, v44, v45
	v_cvt_pk_bf16_f32 v168, v58, v59
	v_cvt_pk_bf16_f32 v169, v60, v61
	s_waitcnt lgkmcnt(14)
	s_nop 0
	v_mfma_f32_16x16x32_bf16 v[170:173], v[152:155], v[166:169], v[170:173]
	s_waitcnt lgkmcnt(13)
	v_mfma_f32_16x16x32_bf16 v[174:177], v[156:159], v[166:169], v[174:177]
	ds_read_b128 v[240:243], v122 offset:19072
	ds_read_b128 v[244:247], v126 offset:8704
	s_waitcnt lgkmcnt(7)
	v_lshl_or_b32 v248, v184, 16, v161
	v_lshl_or_b32 v249, v186, 16, v185
	v_lshl_or_b32 v250, v252, 16, v179
	v_lshl_or_b32 v251, v208, 16, v253
	ds_read_b128 v[128:131], v122 offset:19136
	ds_read_b128 v[132:135], v125 offset:13824
	s_waitcnt lgkmcnt(7)
	v_pk_mul_f32 v[72:73], v[72:73], v[190:191]
	v_pk_mul_f32 v[70:71], v[70:71], v[188:189]
	ds_read_b128 v[136:139], v122 offset:19200
	ds_read_b128 v[140:143], v125 offset:15104
	v_mfma_f32_16x16x32_bf16 v[70:73], v[180:183], v[248:251], v[70:73]
	s_waitcnt lgkmcnt(7)
	v_pk_mul_f32 v[68:69], v[68:69], v[234:235]
	v_pk_mul_f32 v[66:67], v[66:67], v[232:233]
	ds_read_b128 v[144:147], v122 offset:19264
	ds_read_b128 v[148:151], v125 offset:16384
	v_mfma_f32_16x16x32_bf16 v[66:69], v[192:195], v[248:251], v[66:69]
	s_waitcnt lgkmcnt(7)
	v_pk_mul_f32 v[76:77], v[76:77], v[242:243]
	v_pk_mul_f32 v[74:75], v[74:75], v[240:241]
	ds_read_b128 v[152:155], v122 offset:19328
	ds_read_b128 v[156:159], v127 offset:8704
	v_mfma_f32_16x16x32_bf16 v[74:77], v[236:239], v[248:251], v[74:77]
	s_waitcnt lgkmcnt(7)
	v_pk_mul_f32 v[80:81], v[80:81], v[130:131]
	v_pk_mul_f32 v[78:79], v[78:79], v[128:129]
	ds_read_b128 v[162:165], v122 offset:19392
	s_nop 0
	v_mfma_f32_16x16x32_bf16 v[78:81], v[244:247], v[248:251], v[78:81]
	s_waitcnt lgkmcnt(6)
	v_pk_mul_f32 v[64:65], v[64:65], v[138:139]
	v_pk_mul_f32 v[62:63], v[62:63], v[136:137]
	s_nop 1
	v_mfma_f32_16x16x32_bf16 v[62:65], v[132:135], v[248:251], v[62:65]
	s_waitcnt lgkmcnt(4)
	v_pk_mul_f32 v[56:57], v[56:57], v[146:147]
	v_pk_mul_f32 v[54:55], v[54:55], v[144:145]
	s_nop 1
	v_mfma_f32_16x16x32_bf16 v[54:57], v[140:143], v[248:251], v[54:57]
	s_waitcnt lgkmcnt(2)
	v_pk_mul_f32 v[44:45], v[44:45], v[154:155]
	v_pk_mul_f32 v[42:43], v[42:43], v[152:153]
	s_nop 1
	v_mfma_f32_16x16x32_bf16 v[42:45], v[148:151], v[248:251], v[42:45]
	s_waitcnt lgkmcnt(0)
	v_pk_mul_f32 v[60:61], v[60:61], v[164:165]
	v_pk_mul_f32 v[58:59], v[58:59], v[162:163]
	s_nop 1
	v_mfma_f32_16x16x32_bf16 v[58:61], v[156:159], v[248:251], v[58:61]
	v_cvt_pk_bf16_f32 v209, v170, v171
	v_cvt_pk_bf16_f32 v161, v172, v173
	v_cvt_pk_bf16_f32 v184, v174, v175
	v_cvt_pk_bf16_f32 v185, v176, v177
	v_add_co_u32_e32 v166, vcc, s24, v110
	s_nop 1
	v_addc_co_u32_e32 v167, vcc, 0, v111, vcc
	v_add_co_u32_e32 v168, vcc, s26, v110
	s_nop 1
	v_addc_co_u32_e32 v169, vcc, 0, v111, vcc
	global_store_short v[166:167], v209, off offset:-4096
	global_store_short_d16_hi v[166:167], v209, off offset:-2048
	global_store_short v[166:167], v161, off
	global_store_short_d16_hi v[166:167], v161, off offset:2048
	global_store_short v[168:169], v184, off offset:-4096
	global_store_short_d16_hi v[168:169], v184, off offset:-2048
	global_store_short v[168:169], v185, off
	global_store_short_d16_hi v[168:169], v185, off offset:2048
	s_setprio 0
.LBB0_1203:
	s_min_u32 s16, s39, 57
	s_add_i32 s40, s16, 6
	s_mul_i32 s16, s40, 0x38000
	s_waitcnt lgkmcnt(0)
	s_barrier
	s_waitcnt vmcnt(15)
	ds_write_b128 v99, v[2:5]
	s_waitcnt vmcnt(14)
	ds_write_b128 v119, v[10:13] offset:8704
	s_waitcnt vmcnt(13)
	ds_write_b128 v120, v[6:9] offset:18944
	s_waitcnt vmcnt(11)
	ds_write_b128 v121, v[22:25] offset:19456
	v_lshl_add_u64 v[2:3], v[102:103], 0, s[16:17]
	v_lshl_add_u64 v[6:7], v[104:105], 0, s[16:17]
	s_lshl_b32 s40, s40, 12
	s_mov_b32 s41, s17
	global_load_dwordx4 v[2:5], v[2:3], off
	s_nop 0
	global_load_dwordx4 v[10:13], v[6:7], off
	v_lshl_add_u64 v[6:7], v[108:109], 0, s[40:41]
	v_lshl_add_u64 v[22:23], v[106:107], 0, s[16:17]
	global_load_dwordx4 v[6:9], v[6:7], off
	s_nop 0
	s_mov_b64 exec, s[100:101]
	global_load_dwordx4 v[22:25], v[22:23], off
	s_mov_b64 exec, -1
	s_and_b64 vcc, exec, s[2:3]
	v_add_u32_e32 v128, 0x6800, v123
	v_add_u32_e32 v101, 0x7800, v123
	s_cbranch_vccnz .LBB0_1205
	s_setprio 2
	v_add_u32_e32 v160, 0x6800, v123
	v_add_u32_e32 v161, 0x7800, v123
	ds_read2_b64 v[128:131], v160 offset0:192 offset1:196
	ds_read2_b64 v[132:135], v161 offset0:224 offset1:228
	ds_read2_b64 v[136:139], v160 offset0:200 offset1:204
	ds_read2_b64 v[140:143], v161 offset0:232 offset1:236
	ds_read2_b64 v[144:147], v160 offset0:208 offset1:212
	ds_read2_b64 v[148:151], v161 offset0:240 offset1:244
	ds_read2_b64 v[152:155], v160 offset0:216 offset1:220
	ds_read2_b64 v[156:159], v161 offset0:248 offset1:252
	ds_read_u16 v184, v124 offset:47616
	ds_read_u16 v185, v124 offset:47888
	ds_read_u16 v186, v124 offset:48160
	ds_read_u16 v179, v124 offset:48432
	ds_read_u16 v252, v124 offset:48704
	ds_read_u16 v253, v124 offset:48976
	v_cvt_pk_bf16_f32 v162, v70, v71
	v_cvt_pk_bf16_f32 v163, v72, v73
	v_cvt_pk_bf16_f32 v164, v66, v67
	v_cvt_pk_bf16_f32 v165, v68, v69
	s_waitcnt lgkmcnt(13)
	s_nop 0
	v_mfma_f32_16x16x32_bf16 v[170:173], v[128:131], v[162:165], 0
	s_waitcnt lgkmcnt(12)
	v_mfma_f32_16x16x32_bf16 v[174:177], v[132:135], v[162:165], 0
	ds_read_u16 v208, v124 offset:49248
	ds_read_u16 v209, v124 offset:49520
	ds_read_b128 v[180:183], v125 offset:36864
	v_cvt_pk_bf16_f32 v166, v74, v75
	v_cvt_pk_bf16_f32 v167, v76, v77
	v_cvt_pk_bf16_f32 v168, v78, v79
	v_cvt_pk_bf16_f32 v169, v80, v81
	s_waitcnt lgkmcnt(14)
	s_nop 0
	v_mfma_f32_16x16x32_bf16 v[170:173], v[136:139], v[166:169], v[170:173]
	s_waitcnt lgkmcnt(13)
	v_mfma_f32_16x16x32_bf16 v[174:177], v[140:143], v[166:169], v[174:177]
	ds_read_b128 v[188:191], v122 offset:47104
	ds_read_b128 v[192:195], v125 offset:38144
	v_cvt_pk_bf16_f32 v162, v62, v63
	v_cvt_pk_bf16_f32 v163, v64, v65
	v_cvt_pk_bf16_f32 v164, v54, v55
	v_cvt_pk_bf16_f32 v165, v56, v57
	s_waitcnt lgkmcnt(14)
	s_nop 0
	v_mfma_f32_16x16x32_bf16 v[170:173], v[144:147], v[162:165], v[170:173]
	s_waitcnt lgkmcnt(13)
	v_mfma_f32_16x16x32_bf16 v[174:177], v[148:151], v[162:165], v[174:177]
	ds_read_b128 v[232:235], v122 offset:47168
	ds_read_b128 v[236:239], v125 offset:39424
	v_cvt_pk_bf16_f32 v166, v42, v43
	v_cvt_pk_bf16_f32 v167, v44, v45
	v_cvt_pk_bf16_f32 v168, v58, v59
	v_cvt_pk_bf16_f32 v169, v60, v61
	s_waitcnt lgkmcnt(14)
	s_nop 0
	v_mfma_f32_16x16x32_bf16 v[170:173], v[152:155], v[166:169], v[170:173]
	s_waitcnt lgkmcnt(13)
	v_mfma_f32_16x16x32_bf16 v[174:177], v[156:159], v[166:169], v[174:177]
	ds_read_b128 v[240:243], v122 offset:47232
	ds_read_b128 v[244:247], v126 offset:36864
	s_waitcnt lgkmcnt(7)
	v_lshl_or_b32 v248, v185, 16, v184
	v_lshl_or_b32 v249, v179, 16, v186
	v_lshl_or_b32 v250, v253, 16, v252
	v_lshl_or_b32 v251, v209, 16, v208
	ds_read_b128 v[128:131], v122 offset:47296
	ds_read_b128 v[132:135], v125 offset:41984
	s_waitcnt lgkmcnt(7)
	v_pk_mul_f32 v[72:73], v[72:73], v[190:191]
	v_pk_mul_f32 v[70:71], v[70:71], v[188:189]
	ds_read_b128 v[136:139], v122 offset:47360
	ds_read_b128 v[140:143], v125 offset:43264
	v_mfma_f32_16x16x32_bf16 v[70:73], v[180:183], v[248:251], v[70:73]
	s_waitcnt lgkmcnt(7)
	v_pk_mul_f32 v[68:69], v[68:69], v[234:235]
	v_pk_mul_f32 v[66:67], v[66:67], v[232:233]
	ds_read_b128 v[144:147], v122 offset:47424
	ds_read_b128 v[148:151], v125 offset:44544
	v_mfma_f32_16x16x32_bf16 v[66:69], v[192:195], v[248:251], v[66:69]
	s_waitcnt lgkmcnt(7)
	v_pk_mul_f32 v[76:77], v[76:77], v[242:243]
	v_pk_mul_f32 v[74:75], v[74:75], v[240:241]
	ds_read_b128 v[152:155], v122 offset:47488
	ds_read_b128 v[156:159], v127 offset:36864
	v_mfma_f32_16x16x32_bf16 v[74:77], v[236:239], v[248:251], v[74:77]
	s_waitcnt lgkmcnt(7)
	v_pk_mul_f32 v[80:81], v[80:81], v[130:131]
	v_pk_mul_f32 v[78:79], v[78:79], v[128:129]
	ds_read_b128 v[162:165], v122 offset:47552
	s_nop 0
	v_mfma_f32_16x16x32_bf16 v[78:81], v[244:247], v[248:251], v[78:81]
	s_waitcnt lgkmcnt(6)
	v_pk_mul_f32 v[64:65], v[64:65], v[138:139]
	v_pk_mul_f32 v[62:63], v[62:63], v[136:137]
	s_nop 1
	v_mfma_f32_16x16x32_bf16 v[62:65], v[132:135], v[248:251], v[62:65]
	s_waitcnt lgkmcnt(4)
	v_pk_mul_f32 v[56:57], v[56:57], v[146:147]
	v_pk_mul_f32 v[54:55], v[54:55], v[144:145]
	s_nop 1
	v_mfma_f32_16x16x32_bf16 v[54:57], v[140:143], v[248:251], v[54:57]
	s_waitcnt lgkmcnt(2)
	v_pk_mul_f32 v[44:45], v[44:45], v[154:155]
	v_pk_mul_f32 v[42:43], v[42:43], v[152:153]
	s_nop 1
	v_mfma_f32_16x16x32_bf16 v[42:45], v[148:151], v[248:251], v[42:45]
	s_waitcnt lgkmcnt(0)
	v_pk_mul_f32 v[60:61], v[60:61], v[164:165]
	v_pk_mul_f32 v[58:59], v[58:59], v[162:163]
	s_nop 1
	v_mfma_f32_16x16x32_bf16 v[58:61], v[156:159], v[248:251], v[58:61]
	v_cvt_pk_bf16_f32 v101, v170, v171
	v_cvt_pk_bf16_f32 v184, v172, v173
	v_cvt_pk_bf16_f32 v185, v174, v175
	v_cvt_pk_bf16_f32 v186, v176, v177
	v_add_co_u32_e32 v166, vcc, s28, v110
	s_nop 1
	v_addc_co_u32_e32 v167, vcc, 0, v111, vcc
	v_add_co_u32_e32 v168, vcc, s30, v110
	s_nop 1
	v_addc_co_u32_e32 v169, vcc, 0, v111, vcc
	global_store_short v[166:167], v101, off offset:-4096
	global_store_short_d16_hi v[166:167], v101, off offset:-2048
	global_store_short v[166:167], v184, off
	global_store_short_d16_hi v[166:167], v184, off offset:2048
	global_store_short v[168:169], v185, off offset:-4096
	global_store_short_d16_hi v[168:169], v185, off offset:-2048
	global_store_short v[168:169], v186, off
	global_store_short_d16_hi v[168:169], v186, off offset:2048
	s_setprio 0
.LBB0_1205:
	s_min_u32 s16, s39, 56
	s_add_i32 s40, s16, 7
	s_mul_i32 s16, s40, 0x38000
	s_lshl_b32 s40, s40, 12
	s_mov_b32 s41, s17
	s_waitcnt lgkmcnt(0)
	s_barrier
	s_waitcnt vmcnt(14)
	ds_write_b128 v99, v[18:21] offset:28160
	s_waitcnt vmcnt(13)
	ds_write_b128 v119, v[26:29] offset:36864
	s_waitcnt vmcnt(9)
	ds_write_b128 v120, v[46:49] offset:47104
	ds_write_b128 v121, v[38:41] offset:47616
	v_lshl_add_u64 v[18:19], v[102:103], 0, s[16:17]
	v_lshl_add_u64 v[26:27], v[104:105], 0, s[16:17]
	v_lshl_add_u64 v[38:39], v[108:109], 0, s[40:41]
	v_lshl_add_u64 v[40:41], v[106:107], 0, s[16:17]
	global_load_dwordx4 v[18:21], v[18:19], off
	s_nop 0
	global_load_dwordx4 v[26:29], v[26:27], off
	s_nop 0
	global_load_dwordx4 v[46:49], v[38:39], off
	s_nop 0
	s_mov_b64 exec, s[100:101]
	global_load_dwordx4 v[38:41], v[40:41], off
	s_mov_b64 exec, -1
	s_and_b64 vcc, exec, s[2:3]
	s_cbranch_vccnz .LBB0_1207
	s_setprio 2
	v_add_u32_e32 v160, 0x1000, v123
	ds_read2_b64 v[128:131], v123 offset1:4
	ds_read2_b64 v[132:135], v160 offset0:32 offset1:36
	ds_read2_b64 v[136:139], v123 offset0:8 offset1:12
	ds_read2_b64 v[140:143], v160 offset0:40 offset1:44
	ds_read2_b64 v[144:147], v123 offset0:16 offset1:20
	ds_read2_b64 v[148:151], v160 offset0:48 offset1:52
	ds_read2_b64 v[152:155], v123 offset0:24 offset1:28
	ds_read2_b64 v[156:159], v160 offset0:56 offset1:60
	ds_read_u16 v161, v124 offset:19456
	ds_read_u16 v184, v124 offset:19728
	ds_read_u16 v185, v124 offset:20000
	ds_read_u16 v186, v124 offset:20272
	ds_read_u16 v179, v124 offset:20544
	ds_read_u16 v252, v124 offset:20816
	v_cvt_pk_bf16_f32 v162, v70, v71
	v_cvt_pk_bf16_f32 v163, v72, v73
	v_cvt_pk_bf16_f32 v164, v66, v67
	v_cvt_pk_bf16_f32 v165, v68, v69
	s_waitcnt lgkmcnt(13)
	s_nop 0
	v_mfma_f32_16x16x32_bf16 v[170:173], v[128:131], v[162:165], 0
	s_waitcnt lgkmcnt(12)
	v_mfma_f32_16x16x32_bf16 v[174:177], v[132:135], v[162:165], 0
	ds_read_u16 v253, v124 offset:21088
	ds_read_u16 v208, v124 offset:21360
	ds_read_b128 v[180:183], v125 offset:8704
	v_cvt_pk_bf16_f32 v166, v74, v75
	v_cvt_pk_bf16_f32 v167, v76, v77
	v_cvt_pk_bf16_f32 v168, v78, v79
	v_cvt_pk_bf16_f32 v169, v80, v81
	s_waitcnt lgkmcnt(14)
	s_nop 0
	v_mfma_f32_16x16x32_bf16 v[170:173], v[136:139], v[166:169], v[170:173]
	s_waitcnt lgkmcnt(13)
	v_mfma_f32_16x16x32_bf16 v[174:177], v[140:143], v[166:169], v[174:177]
	ds_read_b128 v[188:191], v122 offset:18944
	ds_read_b128 v[192:195], v125 offset:9984
	v_cvt_pk_bf16_f32 v162, v62, v63
	v_cvt_pk_bf16_f32 v163, v64, v65
	v_cvt_pk_bf16_f32 v164, v54, v55
	v_cvt_pk_bf16_f32 v165, v56, v57
	s_waitcnt lgkmcnt(14)
	s_nop 0
	v_mfma_f32_16x16x32_bf16 v[170:173], v[144:147], v[162:165], v[170:173]
	s_waitcnt lgkmcnt(13)
	v_mfma_f32_16x16x32_bf16 v[174:177], v[148:151], v[162:165], v[174:177]
	ds_read_b128 v[232:235], v122 offset:19008
	ds_read_b128 v[236:239], v125 offset:11264
	v_cvt_pk_bf16_f32 v166, v42, v43
	v_cvt_pk_bf16_f32 v167, v44, v45
	v_cvt_pk_bf16_f32 v168, v58, v59
	v_cvt_pk_bf16_f32 v169, v60, v61
	s_waitcnt lgkmcnt(14)
	s_nop 0
	v_mfma_f32_16x16x32_bf16 v[170:173], v[152:155], v[166:169], v[170:173]
	s_waitcnt lgkmcnt(13)
	v_mfma_f32_16x16x32_bf16 v[174:177], v[156:159], v[166:169], v[174:177]
	ds_read_b128 v[240:243], v122 offset:19072
	ds_read_b128 v[244:247], v126 offset:8704
	s_waitcnt lgkmcnt(7)
	v_lshl_or_b32 v248, v184, 16, v161
	v_lshl_or_b32 v249, v186, 16, v185
	v_lshl_or_b32 v250, v252, 16, v179
	v_lshl_or_b32 v251, v208, 16, v253
	ds_read_b128 v[128:131], v122 offset:19136
	ds_read_b128 v[132:135], v125 offset:13824
	s_waitcnt lgkmcnt(7)
	v_pk_mul_f32 v[72:73], v[72:73], v[190:191]
	v_pk_mul_f32 v[70:71], v[70:71], v[188:189]
	ds_read_b128 v[136:139], v122 offset:19200
	ds_read_b128 v[140:143], v125 offset:15104
	v_mfma_f32_16x16x32_bf16 v[70:73], v[180:183], v[248:251], v[70:73]
	s_waitcnt lgkmcnt(7)
	v_pk_mul_f32 v[68:69], v[68:69], v[234:235]
	v_pk_mul_f32 v[66:67], v[66:67], v[232:233]
	ds_read_b128 v[144:147], v122 offset:19264
	ds_read_b128 v[148:151], v125 offset:16384
	v_mfma_f32_16x16x32_bf16 v[66:69], v[192:195], v[248:251], v[66:69]
	s_waitcnt lgkmcnt(7)
	v_pk_mul_f32 v[76:77], v[76:77], v[242:243]
	v_pk_mul_f32 v[74:75], v[74:75], v[240:241]
	ds_read_b128 v[152:155], v122 offset:19328
	ds_read_b128 v[156:159], v127 offset:8704
	v_mfma_f32_16x16x32_bf16 v[74:77], v[236:239], v[248:251], v[74:77]
	s_waitcnt lgkmcnt(7)
	v_pk_mul_f32 v[80:81], v[80:81], v[130:131]
	v_pk_mul_f32 v[78:79], v[78:79], v[128:129]
	ds_read_b128 v[162:165], v122 offset:19392
	s_nop 0
	v_mfma_f32_16x16x32_bf16 v[78:81], v[244:247], v[248:251], v[78:81]
	s_waitcnt lgkmcnt(6)
	v_pk_mul_f32 v[64:65], v[64:65], v[138:139]
	v_pk_mul_f32 v[62:63], v[62:63], v[136:137]
	s_nop 1
	v_mfma_f32_16x16x32_bf16 v[62:65], v[132:135], v[248:251], v[62:65]
	s_waitcnt lgkmcnt(4)
	v_pk_mul_f32 v[56:57], v[56:57], v[146:147]
	v_pk_mul_f32 v[54:55], v[54:55], v[144:145]
	s_nop 1
	v_mfma_f32_16x16x32_bf16 v[54:57], v[140:143], v[248:251], v[54:57]
	s_waitcnt lgkmcnt(2)
	v_pk_mul_f32 v[44:45], v[44:45], v[154:155]
	v_pk_mul_f32 v[42:43], v[42:43], v[152:153]
	s_nop 1
	v_mfma_f32_16x16x32_bf16 v[42:45], v[148:151], v[248:251], v[42:45]
	s_waitcnt lgkmcnt(0)
	v_pk_mul_f32 v[60:61], v[60:61], v[164:165]
	v_pk_mul_f32 v[58:59], v[58:59], v[162:163]
	s_nop 1
	v_mfma_f32_16x16x32_bf16 v[58:61], v[156:159], v[248:251], v[58:61]
	v_cvt_pk_bf16_f32 v209, v170, v171
	v_cvt_pk_bf16_f32 v161, v172, v173
	v_cvt_pk_bf16_f32 v184, v174, v175
	v_cvt_pk_bf16_f32 v185, v176, v177
	v_add_co_u32_e32 v166, vcc, s33, v110
	s_nop 1
	v_addc_co_u32_e32 v167, vcc, 0, v111, vcc
	v_add_co_u32_e32 v168, vcc, s35, v110
	s_nop 1
	v_addc_co_u32_e32 v169, vcc, 0, v111, vcc
	global_store_short v[166:167], v209, off offset:-4096
	global_store_short_d16_hi v[166:167], v209, off offset:-2048
	global_store_short v[166:167], v161, off
	global_store_short_d16_hi v[166:167], v161, off offset:2048
	global_store_short v[168:169], v184, off offset:-4096
	global_store_short_d16_hi v[168:169], v184, off offset:-2048
	global_store_short v[168:169], v185, off
	global_store_short_d16_hi v[168:169], v185, off offset:2048
	s_setprio 0
.LBB0_1207:
	s_min_u32 s16, s39, 55
	s_add_i32 s40, s16, 8
	s_mul_i32 s16, s40, 0x38000
	s_waitcnt lgkmcnt(0)
	s_barrier
	ds_write_b128 v99, v[30:33]
	ds_write_b128 v119, v[34:37] offset:8704
	s_waitcnt vmcnt(12)
	ds_write_b128 v120, v[50:53] offset:18944
	ds_write_b128 v121, v[14:17] offset:19456
	v_lshl_add_u64 v[14:15], v[102:103], 0, s[16:17]
	v_lshl_add_u64 v[16:17], v[104:105], 0, s[16:17]
	s_lshl_b32 s40, s40, 12
	s_mov_b32 s41, s17
	global_load_dwordx4 v[30:33], v[14:15], off
	global_load_dwordx4 v[34:37], v[16:17], off
	v_lshl_add_u64 v[14:15], v[108:109], 0, s[40:41]
	v_lshl_add_u64 v[16:17], v[106:107], 0, s[16:17]
	global_load_dwordx4 v[50:53], v[14:15], off
	s_nop 0
	s_mov_b64 exec, s[100:101]
	global_load_dwordx4 v[14:17], v[16:17], off
	s_mov_b64 exec, -1
	s_and_b64 vcc, exec, s[2:3]
	s_cbranch_vccnz .LBB0_1209
	s_setprio 2
	v_add_u32_e32 v160, 0x6800, v123
	v_add_u32_e32 v161, 0x7800, v123
	ds_read2_b64 v[128:131], v160 offset0:192 offset1:196
	ds_read2_b64 v[132:135], v161 offset0:224 offset1:228
	ds_read2_b64 v[136:139], v160 offset0:200 offset1:204
	ds_read2_b64 v[140:143], v161 offset0:232 offset1:236
	ds_read2_b64 v[144:147], v160 offset0:208 offset1:212
	ds_read2_b64 v[148:151], v161 offset0:240 offset1:244
	ds_read2_b64 v[152:155], v160 offset0:216 offset1:220
	ds_read2_b64 v[156:159], v161 offset0:248 offset1:252
	ds_read_u16 v184, v124 offset:47616
	ds_read_u16 v185, v124 offset:47888
	ds_read_u16 v186, v124 offset:48160
	ds_read_u16 v179, v124 offset:48432
	ds_read_u16 v252, v124 offset:48704
	ds_read_u16 v253, v124 offset:48976
	v_cvt_pk_bf16_f32 v162, v70, v71
	v_cvt_pk_bf16_f32 v163, v72, v73
	v_cvt_pk_bf16_f32 v164, v66, v67
	v_cvt_pk_bf16_f32 v165, v68, v69
	s_waitcnt lgkmcnt(13)
	s_nop 0
	v_mfma_f32_16x16x32_bf16 v[170:173], v[128:131], v[162:165], 0
	s_waitcnt lgkmcnt(12)
	v_mfma_f32_16x16x32_bf16 v[174:177], v[132:135], v[162:165], 0
	ds_read_u16 v208, v124 offset:49248
	ds_read_u16 v209, v124 offset:49520
	ds_read_b128 v[180:183], v125 offset:36864
	v_cvt_pk_bf16_f32 v166, v74, v75
	v_cvt_pk_bf16_f32 v167, v76, v77
	v_cvt_pk_bf16_f32 v168, v78, v79
	v_cvt_pk_bf16_f32 v169, v80, v81
	s_waitcnt lgkmcnt(14)
	s_nop 0
	v_mfma_f32_16x16x32_bf16 v[170:173], v[136:139], v[166:169], v[170:173]
	s_waitcnt lgkmcnt(13)
	v_mfma_f32_16x16x32_bf16 v[174:177], v[140:143], v[166:169], v[174:177]
	ds_read_b128 v[188:191], v122 offset:47104
	ds_read_b128 v[192:195], v125 offset:38144
	v_cvt_pk_bf16_f32 v162, v62, v63
	v_cvt_pk_bf16_f32 v163, v64, v65
	v_cvt_pk_bf16_f32 v164, v54, v55
	v_cvt_pk_bf16_f32 v165, v56, v57
	s_waitcnt lgkmcnt(14)
	s_nop 0
	v_mfma_f32_16x16x32_bf16 v[170:173], v[144:147], v[162:165], v[170:173]
	s_waitcnt lgkmcnt(13)
	v_mfma_f32_16x16x32_bf16 v[174:177], v[148:151], v[162:165], v[174:177]
	ds_read_b128 v[232:235], v122 offset:47168
	ds_read_b128 v[236:239], v125 offset:39424
	v_cvt_pk_bf16_f32 v166, v42, v43
	v_cvt_pk_bf16_f32 v167, v44, v45
	v_cvt_pk_bf16_f32 v168, v58, v59
	v_cvt_pk_bf16_f32 v169, v60, v61
	s_waitcnt lgkmcnt(14)
	s_nop 0
	v_mfma_f32_16x16x32_bf16 v[170:173], v[152:155], v[166:169], v[170:173]
	s_waitcnt lgkmcnt(13)
	v_mfma_f32_16x16x32_bf16 v[174:177], v[156:159], v[166:169], v[174:177]
	ds_read_b128 v[240:243], v122 offset:47232
	ds_read_b128 v[244:247], v126 offset:36864
	s_waitcnt lgkmcnt(7)
	v_lshl_or_b32 v248, v185, 16, v184
	v_lshl_or_b32 v249, v179, 16, v186
	v_lshl_or_b32 v250, v253, 16, v252
	v_lshl_or_b32 v251, v209, 16, v208
	ds_read_b128 v[128:131], v122 offset:47296
	ds_read_b128 v[132:135], v125 offset:41984
	s_waitcnt lgkmcnt(7)
	v_pk_mul_f32 v[72:73], v[72:73], v[190:191]
	v_pk_mul_f32 v[70:71], v[70:71], v[188:189]
	ds_read_b128 v[136:139], v122 offset:47360
	ds_read_b128 v[140:143], v125 offset:43264
	v_mfma_f32_16x16x32_bf16 v[70:73], v[180:183], v[248:251], v[70:73]
	s_waitcnt lgkmcnt(7)
	v_pk_mul_f32 v[68:69], v[68:69], v[234:235]
	v_pk_mul_f32 v[66:67], v[66:67], v[232:233]
	ds_read_b128 v[144:147], v122 offset:47424
	ds_read_b128 v[148:151], v125 offset:44544
	v_mfma_f32_16x16x32_bf16 v[66:69], v[192:195], v[248:251], v[66:69]
	s_waitcnt lgkmcnt(7)
	v_pk_mul_f32 v[76:77], v[76:77], v[242:243]
	v_pk_mul_f32 v[74:75], v[74:75], v[240:241]
	ds_read_b128 v[152:155], v122 offset:47488
	ds_read_b128 v[156:159], v127 offset:36864
	v_mfma_f32_16x16x32_bf16 v[74:77], v[236:239], v[248:251], v[74:77]
	s_waitcnt lgkmcnt(7)
	v_pk_mul_f32 v[80:81], v[80:81], v[130:131]
	v_pk_mul_f32 v[78:79], v[78:79], v[128:129]
	ds_read_b128 v[162:165], v122 offset:47552
	s_nop 0
	v_mfma_f32_16x16x32_bf16 v[78:81], v[244:247], v[248:251], v[78:81]
	s_waitcnt lgkmcnt(6)
	v_pk_mul_f32 v[64:65], v[64:65], v[138:139]
	v_pk_mul_f32 v[62:63], v[62:63], v[136:137]
	s_nop 1
	v_mfma_f32_16x16x32_bf16 v[62:65], v[132:135], v[248:251], v[62:65]
	s_waitcnt lgkmcnt(4)
	v_pk_mul_f32 v[56:57], v[56:57], v[146:147]
	v_pk_mul_f32 v[54:55], v[54:55], v[144:145]
	s_nop 1
	v_mfma_f32_16x16x32_bf16 v[54:57], v[140:143], v[248:251], v[54:57]
	s_waitcnt lgkmcnt(2)
	v_pk_mul_f32 v[44:45], v[44:45], v[154:155]
	v_pk_mul_f32 v[42:43], v[42:43], v[152:153]
	s_nop 1
	v_mfma_f32_16x16x32_bf16 v[42:45], v[148:151], v[248:251], v[42:45]
	s_waitcnt lgkmcnt(0)
	v_pk_mul_f32 v[60:61], v[60:61], v[164:165]
	v_pk_mul_f32 v[58:59], v[58:59], v[162:163]
	s_nop 1
	v_mfma_f32_16x16x32_bf16 v[58:61], v[156:159], v[248:251], v[58:61]
	v_cvt_pk_bf16_f32 v101, v170, v171
	v_cvt_pk_bf16_f32 v184, v172, v173
	v_cvt_pk_bf16_f32 v185, v174, v175
	v_cvt_pk_bf16_f32 v186, v176, v177
	v_add_co_u32_e32 v166, vcc, s37, v110
	s_nop 1
	v_addc_co_u32_e32 v167, vcc, 0, v111, vcc
	v_add_co_u32_e32 v168, vcc, s38, v110
	s_nop 1
	v_addc_co_u32_e32 v169, vcc, 0, v111, vcc
	global_store_short v[166:167], v101, off offset:-4096
	global_store_short_d16_hi v[166:167], v101, off offset:-2048
	global_store_short v[166:167], v184, off
	global_store_short_d16_hi v[166:167], v184, off offset:2048
	global_store_short v[168:169], v185, off offset:-4096
	global_store_short_d16_hi v[168:169], v185, off offset:-2048
	global_store_short v[168:169], v186, off
	global_store_short_d16_hi v[168:169], v186, off offset:2048
	s_setprio 0

.LBB0_1216:
	s_min_u32 s2, s28, 58
	s_add_i32 s2, s2, 5
	s_mul_i32 s8, s2, 0x38000
	s_lshl_b32 s2, s2, 12
	s_mov_b32 s3, s9
	v_lshl_add_u64 v[66:67], v[82:83], 0, s[8:9]
	v_lshl_add_u64 v[70:71], v[84:85], 0, s[8:9]
	v_lshl_add_u64 v[74:75], v[86:87], 0, s[2:3]
	v_lshl_add_u64 v[78:79], v[88:89], 0, s[8:9]
	global_load_dwordx4 v[66:69], v[66:67], off
	s_nop 0
	global_load_dwordx4 v[70:73], v[70:71], off
	s_nop 0
	global_load_dwordx4 v[74:77], v[74:75], off
	s_nop 0
	s_mov_b64 exec, s[100:101]
	global_load_dwordx4 v[78:81], v[78:79], off offset:1024
	s_mov_b64 exec, -1
	v_cndmask_b32_e64 v102, 0, 1, s[6:7]
	v_cmp_ne_u32_e64 s[2:3], 1, v102
	s_andn2_b64 vcc, exec, s[6:7]
	v_add_u32_e32 v104, 0x800, v97
	s_cbranch_vccnz .LBB0_1218
	s_setprio 2
	ds_read2_b64 v[106:109], v97 offset1:4
	ds_read2_b64 v[118:121], v104 offset0:32 offset1:36
	ds_read2_b64 v[122:125], v97 offset0:8 offset1:12
	v_cvt_pk_bf16_f32 v114, v2, v3
	v_cvt_pk_bf16_f32 v115, v4, v5
	v_cvt_pk_bf16_f32 v116, v62, v63
	v_cvt_pk_bf16_f32 v117, v64, v65
	v_cvt_pk_bf16_f32 v126, v54, v55
	v_cvt_pk_bf16_f32 v127, v56, v57
	s_waitcnt lgkmcnt(2)
	v_mfma_f32_16x16x32_bf16 v[106:109], v[106:109], v[114:117], 0
	v_cvt_pk_bf16_f32 v128, v58, v59
	v_cvt_pk_bf16_f32 v129, v60, v61
	s_waitcnt lgkmcnt(1)
	v_mfma_f32_16x16x32_bf16 v[114:117], v[118:121], v[114:117], 0
	ds_read2_b64 v[118:121], v104 offset0:40 offset1:44
	ds_read_u16 v102, v99 offset:19456
	ds_read_u16 v103, v99 offset:20544
	ds_read_u16 v105, v99 offset:20816
	ds_read_u16 v110, v99 offset:21088
	ds_read_u16 v111, v99 offset:21360
	ds_read_u16 v113, v99 offset:19728
	ds_read_u16 v130, v99 offset:20000
	ds_read_u16 v131, v99 offset:20272
	s_waitcnt lgkmcnt(9)
	v_mfma_f32_16x16x32_bf16 v[106:109], v[122:125], v[126:129], v[106:109]
	ds_read_b128 v[122:125], v100 offset:8704
	s_waitcnt lgkmcnt(9)
	v_mfma_f32_16x16x32_bf16 v[114:117], v[118:121], v[126:129], v[114:117]
	ds_read_b128 v[126:129], v96 offset:18944
	s_waitcnt lgkmcnt(2)
	v_perm_b32 v119, v131, v130, s14
	ds_read_b128 v[130:133], v100 offset:9984
	ds_read_b128 v[134:137], v96 offset:19008
	v_perm_b32 v121, v111, v110, s14
	v_perm_b32 v120, v105, v103, s14
	v_perm_b32 v118, v113, v102, s14
	s_waitcnt lgkmcnt(2)
	v_pk_mul_f32 v[4:5], v[4:5], v[128:129]
	v_pk_mul_f32 v[2:3], v[2:3], v[126:127]
	s_waitcnt lgkmcnt(0)
	v_pk_mul_f32 v[64:65], v[64:65], v[136:137]
	v_pk_mul_f32 v[62:63], v[62:63], v[134:135]
	v_mfma_f32_16x16x32_bf16 v[2:5], v[122:125], v[118:121], v[2:5]
	ds_read_b128 v[122:125], v100 offset:11264
	ds_read_b128 v[134:137], v101 offset:8704
	ds_read_b128 v[126:129], v96 offset:19072
	v_mfma_f32_16x16x32_bf16 v[62:65], v[130:133], v[118:121], v[62:65]
	ds_read_b128 v[130:133], v96 offset:19136
	v_cvt_pk_bf16_f32 v102, v106, v107
	global_store_short v[90:91], v102, off
	global_store_short_d16_hi v[90:91], v102, off offset:2048
	v_add_co_u32_e32 v102, vcc, s13, v90
	v_cvt_pk_bf16_f32 v105, v108, v109
	s_nop 0
	v_addc_co_u32_e32 v103, vcc, 0, v91, vcc
	s_waitcnt lgkmcnt(1)
	v_pk_mul_f32 v[56:57], v[56:57], v[128:129]
	v_pk_mul_f32 v[54:55], v[54:55], v[126:127]
	s_waitcnt lgkmcnt(0)
	v_pk_mul_f32 v[60:61], v[60:61], v[132:133]
	v_pk_mul_f32 v[58:59], v[58:59], v[130:131]
	global_store_short v[102:103], v105, off
	global_store_short_d16_hi v[102:103], v105, off offset:2048
	v_add_co_u32_e32 v102, vcc, s15, v90
	v_mfma_f32_16x16x32_bf16 v[54:57], v[122:125], v[118:121], v[54:57]
	s_nop 0
	v_addc_co_u32_e32 v103, vcc, 0, v91, vcc
	v_add_co_u32_e32 v106, vcc, s16, v90
	v_mfma_f32_16x16x32_bf16 v[58:61], v[134:137], v[118:121], v[58:61]
	v_cvt_pk_bf16_f32 v105, v114, v115
	v_addc_co_u32_e32 v107, vcc, 0, v91, vcc
	global_store_short v[106:107], v105, off offset:-4096
	global_store_short_d16_hi v[102:103], v105, off offset:2048
	v_cvt_pk_bf16_f32 v102, v116, v117
	global_store_short v[106:107], v102, off
	global_store_short_d16_hi v[106:107], v102, off offset:2048
	s_setprio 0
.LBB0_1218:
	s_min_u32 s8, s28, 57
	s_add_i32 s29, s8, 6
	s_mul_i32 s8, s29, 0x38000
	s_lshl_b32 s30, s29, 12
	s_mov_b32 s31, s9
	s_waitcnt lgkmcnt(0)
	s_barrier
	s_waitcnt vmcnt(15)
	ds_write_b128 v92, v[6:9]
	s_waitcnt vmcnt(14)
	ds_write_b128 v93, v[10:13] offset:8704
	s_waitcnt vmcnt(13)
	ds_write_b128 v94, v[14:17] offset:18944
	s_waitcnt vmcnt(12)
	ds_write_b128 v95, v[22:25] offset:19456
	v_lshl_add_u64 v[6:7], v[82:83], 0, s[8:9]
	v_lshl_add_u64 v[10:11], v[84:85], 0, s[8:9]
	v_lshl_add_u64 v[14:15], v[86:87], 0, s[30:31]
	v_lshl_add_u64 v[22:23], v[88:89], 0, s[8:9]
	global_load_dwordx4 v[6:9], v[6:7], off
	s_nop 0
	global_load_dwordx4 v[10:13], v[10:11], off
	s_nop 0
	global_load_dwordx4 v[14:17], v[14:15], off
	s_nop 0
	s_mov_b64 exec, s[100:101]
	global_load_dwordx4 v[22:25], v[22:23], off offset:1024
	s_mov_b64 exec, -1
	s_and_b64 vcc, exec, s[2:3]
	v_add_u32_e32 v103, 0x6800, v97
	v_add_u32_e32 v102, 0x7000, v97
	s_cbranch_vccnz .LBB0_1220
	s_setprio 2
	ds_read2_b64 v[106:109], v103 offset0:192 offset1:196
	ds_read2_b64 v[118:121], v102 offset0:224 offset1:228
	ds_read2_b64 v[122:125], v103 offset0:200 offset1:204
	v_cvt_pk_bf16_f32 v114, v2, v3
	v_cvt_pk_bf16_f32 v115, v4, v5
	v_cvt_pk_bf16_f32 v116, v62, v63
	v_cvt_pk_bf16_f32 v117, v64, v65
	v_cvt_pk_bf16_f32 v126, v54, v55
	v_cvt_pk_bf16_f32 v127, v56, v57
	s_waitcnt lgkmcnt(2)
	v_mfma_f32_16x16x32_bf16 v[106:109], v[106:109], v[114:117], 0
	v_cvt_pk_bf16_f32 v128, v58, v59
	v_cvt_pk_bf16_f32 v129, v60, v61
	s_waitcnt lgkmcnt(1)
	v_mfma_f32_16x16x32_bf16 v[114:117], v[118:121], v[114:117], 0
	s_waitcnt lgkmcnt(0)
	v_mfma_f32_16x16x32_bf16 v[106:109], v[122:125], v[126:129], v[106:109]
	ds_read2_b64 v[118:121], v102 offset0:232 offset1:236
	ds_read_u16 v105, v99 offset:47616
	ds_read_u16 v110, v99 offset:48704
	ds_read_u16 v111, v99 offset:48976
	ds_read_u16 v113, v99 offset:49248
	ds_read_u16 v122, v99 offset:49520
	ds_read_u16 v130, v99 offset:47888
	ds_read_u16 v131, v99 offset:48160
	ds_read_u16 v132, v99 offset:48432
	s_waitcnt lgkmcnt(8)
	v_mfma_f32_16x16x32_bf16 v[114:117], v[118:121], v[126:129], v[114:117]
	s_waitcnt lgkmcnt(3)
	v_perm_b32 v121, v122, v113, s14
	ds_read_b128 v[122:125], v100 offset:36864
	ds_read_b128 v[126:129], v96 offset:47104
	s_waitcnt lgkmcnt(2)
	v_perm_b32 v119, v132, v131, s14
	v_perm_b32 v118, v130, v105, s14
	ds_read_b128 v[130:133], v100 offset:38144
	ds_read_b128 v[134:137], v96 offset:47168
	v_perm_b32 v120, v111, v110, s14
	s_waitcnt lgkmcnt(2)
	v_pk_mul_f32 v[4:5], v[4:5], v[128:129]
	v_pk_mul_f32 v[2:3], v[2:3], v[126:127]
	ds_read_b128 v[126:129], v96 offset:47232
	s_waitcnt lgkmcnt(1)
	v_pk_mul_f32 v[64:65], v[64:65], v[136:137]
	v_mfma_f32_16x16x32_bf16 v[2:5], v[122:125], v[118:121], v[2:5]
	ds_read_b128 v[122:125], v100 offset:39424
	v_pk_mul_f32 v[62:63], v[62:63], v[134:135]
	ds_read_b128 v[134:137], v101 offset:36864
	v_cvt_pk_bf16_f32 v105, v106, v107
	v_mfma_f32_16x16x32_bf16 v[62:65], v[130:133], v[118:121], v[62:65]
	ds_read_b128 v[130:133], v96 offset:47296
	v_add_co_u32_e32 v106, vcc, s17, v90
	s_waitcnt lgkmcnt(3)
	v_pk_mul_f32 v[56:57], v[56:57], v[128:129]
	v_addc_co_u32_e32 v107, vcc, 0, v91, vcc
	v_add_co_u32_e32 v110, vcc, s18, v90
	v_pk_mul_f32 v[54:55], v[54:55], v[126:127]
	s_nop 0
	v_addc_co_u32_e32 v111, vcc, 0, v91, vcc
	s_waitcnt lgkmcnt(0)
	v_pk_mul_f32 v[60:61], v[60:61], v[132:133]
	v_pk_mul_f32 v[58:59], v[58:59], v[130:131]
	global_store_short v[110:111], v105, off offset:-4096
	global_store_short_d16_hi v[106:107], v105, off offset:2048
	v_add_co_u32_e32 v106, vcc, s19, v90
	v_mfma_f32_16x16x32_bf16 v[54:57], v[122:125], v[118:121], v[54:57]
	s_nop 0
	v_addc_co_u32_e32 v107, vcc, 0, v91, vcc
	v_cvt_pk_bf16_f32 v105, v108, v109
	v_mfma_f32_16x16x32_bf16 v[58:61], v[134:137], v[118:121], v[58:61]
	v_add_co_u32_e32 v108, vcc, s20, v90
	global_store_short v[110:111], v105, off
	global_store_short_d16_hi v[110:111], v105, off offset:2048
	v_cvt_pk_bf16_f32 v105, v114, v115
	v_addc_co_u32_e32 v109, vcc, 0, v91, vcc
	global_store_short v[108:109], v105, off offset:-4096
	global_store_short_d16_hi v[106:107], v105, off offset:2048
	v_cvt_pk_bf16_f32 v105, v116, v117
	global_store_short v[108:109], v105, off
	global_store_short_d16_hi v[108:109], v105, off offset:2048
	s_setprio 0
.LBB0_1220:
	s_min_u32 s8, s28, 56
	s_add_i32 s29, s8, 7
	s_mul_i32 s8, s29, 0x38000
	s_lshl_b32 s30, s29, 12
	s_mov_b32 s31, s9
	s_waitcnt lgkmcnt(0)
	s_barrier
	s_waitcnt vmcnt(15)
	ds_write_b128 v92, v[18:21] offset:28160
	s_waitcnt vmcnt(14)
	ds_write_b128 v93, v[26:29] offset:36864
	s_waitcnt vmcnt(10)
	ds_write_b128 v94, v[42:45] offset:47104
	ds_write_b128 v95, v[30:33] offset:47616
	v_lshl_add_u64 v[18:19], v[82:83], 0, s[8:9]
	v_lshl_add_u64 v[26:27], v[84:85], 0, s[8:9]
	v_lshl_add_u64 v[30:31], v[86:87], 0, s[30:31]
	v_lshl_add_u64 v[32:33], v[88:89], 0, s[8:9]
	global_load_dwordx4 v[18:21], v[18:19], off
	s_nop 0
	global_load_dwordx4 v[26:29], v[26:27], off
	s_nop 0
	global_load_dwordx4 v[42:45], v[30:31], off
	s_nop 0
	s_mov_b64 exec, s[100:101]
	global_load_dwordx4 v[30:33], v[32:33], off offset:1024
	s_mov_b64 exec, -1
	s_and_b64 vcc, exec, s[2:3]
	s_cbranch_vccnz .LBB0_1222
	s_setprio 2
	ds_read2_b64 v[106:109], v97 offset1:4
	ds_read2_b64 v[118:121], v104 offset0:32 offset1:36
	ds_read2_b64 v[122:125], v97 offset0:8 offset1:12
	v_cvt_pk_bf16_f32 v114, v2, v3
	v_cvt_pk_bf16_f32 v115, v4, v5
	v_cvt_pk_bf16_f32 v116, v62, v63
	v_cvt_pk_bf16_f32 v117, v64, v65
	v_cvt_pk_bf16_f32 v126, v54, v55
	v_cvt_pk_bf16_f32 v127, v56, v57
	s_waitcnt lgkmcnt(2)
	v_mfma_f32_16x16x32_bf16 v[106:109], v[106:109], v[114:117], 0
	v_cvt_pk_bf16_f32 v128, v58, v59
	v_cvt_pk_bf16_f32 v129, v60, v61
	s_waitcnt lgkmcnt(1)
	v_mfma_f32_16x16x32_bf16 v[114:117], v[118:121], v[114:117], 0
	ds_read2_b64 v[118:121], v104 offset0:40 offset1:44
	ds_read_u16 v104, v99 offset:19456
	ds_read_u16 v105, v99 offset:20544
	ds_read_u16 v110, v99 offset:20816
	ds_read_u16 v111, v99 offset:21088
	ds_read_u16 v113, v99 offset:21360
	ds_read_u16 v130, v99 offset:19728
	ds_read_u16 v131, v99 offset:20000
	ds_read_u16 v132, v99 offset:20272
	s_waitcnt lgkmcnt(9)
	v_mfma_f32_16x16x32_bf16 v[106:109], v[122:125], v[126:129], v[106:109]
	ds_read_b128 v[122:125], v100 offset:8704
	s_waitcnt lgkmcnt(9)
	v_mfma_f32_16x16x32_bf16 v[114:117], v[118:121], v[126:129], v[114:117]
	ds_read_b128 v[126:129], v96 offset:18944
	s_waitcnt lgkmcnt(2)
	v_perm_b32 v119, v132, v131, s14
	v_perm_b32 v118, v130, v104, s14
	ds_read_b128 v[130:133], v100 offset:9984
	ds_read_b128 v[134:137], v96 offset:19008
	v_perm_b32 v121, v113, v111, s14
	v_perm_b32 v120, v110, v105, s14
	s_waitcnt lgkmcnt(2)
	v_pk_mul_f32 v[4:5], v[4:5], v[128:129]
	v_pk_mul_f32 v[2:3], v[2:3], v[126:127]
	s_waitcnt lgkmcnt(0)
	v_pk_mul_f32 v[64:65], v[64:65], v[136:137]
	v_pk_mul_f32 v[62:63], v[62:63], v[134:135]
	v_mfma_f32_16x16x32_bf16 v[2:5], v[122:125], v[118:121], v[2:5]
	ds_read_b128 v[122:125], v100 offset:11264
	ds_read_b128 v[134:137], v101 offset:8704
	ds_read_b128 v[126:129], v96 offset:19072
	v_mfma_f32_16x16x32_bf16 v[62:65], v[130:133], v[118:121], v[62:65]
	ds_read_b128 v[130:133], v96 offset:19136
	v_add_co_u32_e32 v104, vcc, s21, v90
	v_cvt_pk_bf16_f32 v110, v106, v107
	s_nop 0
	v_addc_co_u32_e32 v105, vcc, 0, v91, vcc
	v_add_co_u32_e32 v106, vcc, s22, v90
	s_waitcnt lgkmcnt(1)
	v_pk_mul_f32 v[56:57], v[56:57], v[128:129]
	v_addc_co_u32_e32 v107, vcc, 0, v91, vcc
	global_store_short v[106:107], v110, off offset:-4096
	global_store_short_d16_hi v[104:105], v110, off offset:2048
	v_cvt_pk_bf16_f32 v104, v108, v109
	v_pk_mul_f32 v[54:55], v[54:55], v[126:127]
	s_waitcnt lgkmcnt(0)
	v_pk_mul_f32 v[60:61], v[60:61], v[132:133]
	v_pk_mul_f32 v[58:59], v[58:59], v[130:131]
	global_store_short v[106:107], v104, off
	global_store_short_d16_hi v[106:107], v104, off offset:2048
	v_add_co_u32_e32 v104, vcc, s23, v90
	v_mfma_f32_16x16x32_bf16 v[54:57], v[122:125], v[118:121], v[54:57]
	s_nop 0
	v_addc_co_u32_e32 v105, vcc, 0, v91, vcc
	v_add_co_u32_e32 v106, vcc, s24, v90
	v_mfma_f32_16x16x32_bf16 v[58:61], v[134:137], v[118:121], v[58:61]
	v_cvt_pk_bf16_f32 v108, v114, v115
	v_addc_co_u32_e32 v107, vcc, 0, v91, vcc
	global_store_short v[106:107], v108, off offset:-4096
	global_store_short_d16_hi v[104:105], v108, off offset:2048
	v_cvt_pk_bf16_f32 v104, v116, v117
	global_store_short v[106:107], v104, off
	global_store_short_d16_hi v[106:107], v104, off offset:2048
	s_setprio 0
.LBB0_1222:
	s_min_u32 s8, s28, 55
	s_add_i32 s29, s8, 8
	s_mul_i32 s8, s29, 0x38000
	s_lshl_b32 s30, s29, 12
	s_mov_b32 s31, s9
	s_waitcnt lgkmcnt(0)
	s_barrier
	ds_write_b128 v92, v[34:37]
	ds_write_b128 v93, v[38:41] offset:8704
	s_waitcnt vmcnt(13)
	ds_write_b128 v94, v[46:49] offset:18944
	s_waitcnt vmcnt(12)
	ds_write_b128 v95, v[50:53] offset:19456
	v_lshl_add_u64 v[34:35], v[82:83], 0, s[8:9]
	v_lshl_add_u64 v[38:39], v[84:85], 0, s[8:9]
	v_lshl_add_u64 v[46:47], v[86:87], 0, s[30:31]
	v_lshl_add_u64 v[50:51], v[88:89], 0, s[8:9]
	global_load_dwordx4 v[34:37], v[34:35], off
	s_nop 0
	global_load_dwordx4 v[38:41], v[38:39], off
	s_nop 0
	global_load_dwordx4 v[46:49], v[46:47], off
	s_nop 0
	s_mov_b64 exec, s[100:101]
	global_load_dwordx4 v[50:53], v[50:51], off offset:1024
	s_mov_b64 exec, -1
	s_and_b64 vcc, exec, s[2:3]
	s_cbranch_vccnz .LBB0_1224
	s_setprio 2
	ds_read2_b64 v[104:107], v103 offset0:192 offset1:196
	ds_read2_b64 v[114:117], v102 offset0:224 offset1:228
	ds_read2_b64 v[118:121], v103 offset0:200 offset1:204
	v_cvt_pk_bf16_f32 v108, v2, v3
	v_cvt_pk_bf16_f32 v109, v4, v5
	v_cvt_pk_bf16_f32 v110, v62, v63
	v_cvt_pk_bf16_f32 v111, v64, v65
	v_cvt_pk_bf16_f32 v122, v54, v55
	v_cvt_pk_bf16_f32 v123, v56, v57
	s_waitcnt lgkmcnt(2)
	v_mfma_f32_16x16x32_bf16 v[104:107], v[104:107], v[108:111], 0
	v_cvt_pk_bf16_f32 v124, v58, v59
	v_cvt_pk_bf16_f32 v125, v60, v61
	s_waitcnt lgkmcnt(1)
	v_mfma_f32_16x16x32_bf16 v[108:111], v[114:117], v[108:111], 0
	s_waitcnt lgkmcnt(0)
	v_mfma_f32_16x16x32_bf16 v[104:107], v[118:121], v[122:125], v[104:107]
	ds_read2_b64 v[114:117], v102 offset0:232 offset1:236
	ds_read_u16 v102, v99 offset:47616
	ds_read_u16 v103, v99 offset:48704
	ds_read_u16 v113, v99 offset:48976
	ds_read_u16 v118, v99 offset:49248
	ds_read_u16 v119, v99 offset:49520
	ds_read_u16 v126, v99 offset:47888
	ds_read_u16 v127, v99 offset:48160
	ds_read_u16 v128, v99 offset:48432
	s_waitcnt lgkmcnt(8)
	v_mfma_f32_16x16x32_bf16 v[108:111], v[114:117], v[122:125], v[108:111]
	s_waitcnt lgkmcnt(3)
	v_perm_b32 v117, v119, v118, s14
	ds_read_b128 v[118:121], v100 offset:36864
	ds_read_b128 v[122:125], v96 offset:47104
	s_waitcnt lgkmcnt(2)
	v_perm_b32 v115, v128, v127, s14
	v_perm_b32 v114, v126, v102, s14
	ds_read_b128 v[126:129], v100 offset:38144
	ds_read_b128 v[130:133], v96 offset:47168
	v_perm_b32 v116, v113, v103, s14
	s_waitcnt lgkmcnt(2)
	v_pk_mul_f32 v[4:5], v[4:5], v[124:125]
	v_pk_mul_f32 v[2:3], v[2:3], v[122:123]
	ds_read_b128 v[122:125], v96 offset:47232
	s_waitcnt lgkmcnt(1)
	v_pk_mul_f32 v[64:65], v[64:65], v[132:133]
	v_mfma_f32_16x16x32_bf16 v[2:5], v[118:121], v[114:117], v[2:5]
	ds_read_b128 v[118:121], v100 offset:39424
	v_pk_mul_f32 v[62:63], v[62:63], v[130:131]
	ds_read_b128 v[130:133], v101 offset:36864
	v_add_co_u32_e32 v102, vcc, s25, v90
	v_mfma_f32_16x16x32_bf16 v[62:65], v[126:129], v[114:117], v[62:65]
	ds_read_b128 v[126:129], v96 offset:47296
	v_addc_co_u32_e32 v103, vcc, 0, v91, vcc
	v_cvt_pk_bf16_f32 v113, v104, v105
	v_add_co_u32_e32 v104, vcc, s26, v90
	s_waitcnt lgkmcnt(3)
	v_pk_mul_f32 v[56:57], v[56:57], v[124:125]
	v_addc_co_u32_e32 v105, vcc, 0, v91, vcc
	global_store_short v[104:105], v113, off offset:-4096
	global_store_short_d16_hi v[102:103], v113, off offset:2048
	v_cvt_pk_bf16_f32 v102, v106, v107
	v_pk_mul_f32 v[54:55], v[54:55], v[122:123]
	s_waitcnt lgkmcnt(0)
	v_pk_mul_f32 v[60:61], v[60:61], v[128:129]
	v_pk_mul_f32 v[58:59], v[58:59], v[126:127]
	global_store_short v[104:105], v102, off
	global_store_short_d16_hi v[104:105], v102, off offset:2048
	v_add_co_u32_e32 v102, vcc, s12, v90
	v_mfma_f32_16x16x32_bf16 v[54:57], v[118:121], v[114:117], v[54:57]
	s_nop 0
	v_addc_co_u32_e32 v103, vcc, 0, v91, vcc
	v_add_co_u32_e32 v104, vcc, s27, v90
	v_mfma_f32_16x16x32_bf16 v[58:61], v[130:133], v[114:117], v[58:61]
	v_cvt_pk_bf16_f32 v106, v108, v109
	v_addc_co_u32_e32 v105, vcc, 0, v91, vcc
	global_store_short v[104:105], v106, off offset:-4096
	global_store_short_d16_hi v[102:103], v106, off offset:2048
	v_cvt_pk_bf16_f32 v102, v110, v111
	global_store_short v[104:105], v102, off
	global_store_short_d16_hi v[104:105], v102, off offset:2048
	s_setprio 0
